# first DMA op of the B+A read segments (the one the next strict wait needs) issued before the LDS reads
# speedup vs baseline: 1.0131x; 1.0062x over previous
.LBB0_415:
	v_writelane_b32 v250, s5, 0
	v_writelane_b32 v250, s23, 1
	v_writelane_b32 v250, s26, 2
	v_writelane_b32 v250, s27, 3
	v_writelane_b32 v250, s28, 4
	v_writelane_b32 v250, s29, 5
	v_writelane_b32 v250, s42, 6
	v_writelane_b32 v250, s43, 7
	v_writelane_b32 v250, s44, 8
	v_writelane_b32 v250, s45, 9
	v_writelane_b32 v250, s46, 10
	v_writelane_b32 v250, s47, 11
	v_writelane_b32 v250, s48, 12
	v_writelane_b32 v250, s49, 13
	v_writelane_b32 v250, s50, 14
	v_writelane_b32 v250, s51, 15
	v_writelane_b32 v250, s53, 16
	v_writelane_b32 v250, s54, 17
	v_writelane_b32 v250, s55, 18
	v_writelane_b32 v250, s56, 19
	v_writelane_b32 v250, s57, 20
	v_writelane_b32 v250, s58, 21
	v_writelane_b32 v250, s59, 22
	v_writelane_b32 v250, s60, 23
	v_writelane_b32 v250, s61, 24
	v_writelane_b32 v250, s63, 25
	v_writelane_b32 v250, s64, 26
	v_writelane_b32 v250, s65, 27
	s_add_i32 s53, s90, 0x80
	s_add_i32 s54, s52, -4
	s_add_i32 s55, s52, -3
	s_mov_b32 s56, s48
	s_add_i32 s57, s56, 0x2000
	s_add_i32 s58, s56, 0x4000
	s_add_i32 s59, s56, 0x6000
	s_add_i32 s60, s56, 0x8000
	s_add_i32 s61, s56, 0xa000
	v_readfirstlane_b32 s42, v6
	v_readfirstlane_b32 s43, v7
	v_readfirstlane_b32 s28, v4
	v_readfirstlane_b32 s29, v5
	v_readfirstlane_b32 s26, v146
	v_readfirstlane_b32 s5, v147
	v_readfirstlane_b32 s27, v148
	v_readfirstlane_b32 s23, v149
	s_add_u32 s28, s28, 0x100
	s_addc_u32 s29, s29, 0
	s_mov_b32 s63, -2
	v_mov_b32_e32 v4, 0
	s_add_u32 s44, s42, 0x100
	s_addc_u32 s45, s43, 0
	s_cmp_eq_u32 s63, s54
	s_cselect_b32 s50, s26, s44
	s_cselect_b32 s51, s5, s45
	s_cselect_b32 s48, s27, s28
	s_cselect_b32 s49, s23, s29
	s_add_i32 s64, 0, 0x10000
	s_add_u32 s46, s42, 0x80
	s_addc_u32 s47, s43, 0
	s_add_u32 s42, s42, s53
	s_addc_u32 s43, s43, 0
	s_mov_b32 m0, s60
	s_nop 0
	global_load_lds_dwordx4 v0, s[46:47]
	s_mov_b32 m0, s61
	s_nop 0
	global_load_lds_dwordx4 v142, s[46:47]
	v_add_u32_e32 v187, s64, v3
	s_add_i32 s65, 0, 0x14000
	ds_read_b128 v[164:167], v187
	ds_read_b128 v[168:171], v187 offset:1024
	ds_read_b128 v[188:191], v187 offset:2048
	ds_read_b128 v[192:195], v187 offset:3072
	v_add_u32_e32 v187, s65, v3
	ds_read_b128 v[196:199], v187
	ds_read_b128 v[200:203], v187 offset:1024
	ds_read_b128 v[204:207], v187 offset:2048
	ds_read_b128 v[208:211], v187 offset:3072
	s_add_i32 m0, s56, 0xc000
	s_nop 0
	global_load_lds_dwordx4 v0, s[42:43]
	s_add_i32 m0, s56, 0xe000
	s_nop 0
	global_load_lds_dwordx4 v142, s[42:43]
	ds_read_b128 v[212:215], v160
	ds_read_b128 v[216:219], v160 offset:1024
	ds_read_b128 v[220:223], v160 offset:2048
	ds_read_b128 v[224:227], v160 offset:3072
	ds_read_b128 v[228:231], v160 offset:4096
	ds_read_b128 v[232:235], v160 offset:5120
	ds_read_b128 v[236:239], v160 offset:6144
	ds_read_b128 v[240:243], v160 offset:7168
	s_waitcnt vmcnt(8)
	s_waitcnt lgkmcnt(8)
	s_barrier
	s_setprio 1
	s_waitcnt lgkmcnt(0)
	v_mfma_f32_16x16x32_bf16 v[128:131], v[164:167], v[212:215], 0
	v_mfma_f32_16x16x32_bf16 v[124:127], v[188:191], v[212:215], 0
	v_mfma_f32_16x16x32_bf16 v[112:115], v[164:167], v[220:223], 0
	v_mfma_f32_16x16x32_bf16 v[108:111], v[188:191], v[220:223], 0
	v_mfma_f32_16x16x32_bf16 v[96:99], v[164:167], v[228:231], 0
	v_mfma_f32_16x16x32_bf16 v[92:95], v[188:191], v[228:231], 0
	v_mfma_f32_16x16x32_bf16 v[80:83], v[164:167], v[236:239], 0
	v_mfma_f32_16x16x32_bf16 v[76:79], v[188:191], v[236:239], 0
	v_mfma_f32_16x16x32_bf16 v[128:131], v[168:171], v[216:219], v[128:131]
	v_mfma_f32_16x16x32_bf16 v[124:127], v[192:195], v[216:219], v[124:127]
	v_mfma_f32_16x16x32_bf16 v[112:115], v[168:171], v[224:227], v[112:115]
	v_mfma_f32_16x16x32_bf16 v[108:111], v[192:195], v[224:227], v[108:111]
	v_mfma_f32_16x16x32_bf16 v[96:99], v[168:171], v[232:235], v[96:99]
	v_mfma_f32_16x16x32_bf16 v[92:95], v[192:195], v[232:235], v[92:95]
	v_mfma_f32_16x16x32_bf16 v[80:83], v[168:171], v[240:243], v[80:83]
	v_mfma_f32_16x16x32_bf16 v[76:79], v[192:195], v[240:243], v[76:79]
	s_setprio 0
	s_setprio 1
	v_mfma_f32_16x16x32_bf16 v[120:123], v[196:199], v[212:215], 0
	v_mfma_f32_16x16x32_bf16 v[116:119], v[204:207], v[212:215], 0
	v_mfma_f32_16x16x32_bf16 v[104:107], v[196:199], v[220:223], 0
	v_mfma_f32_16x16x32_bf16 v[100:103], v[204:207], v[220:223], 0
	v_mfma_f32_16x16x32_bf16 v[88:91], v[196:199], v[228:231], 0
	v_mfma_f32_16x16x32_bf16 v[84:87], v[204:207], v[228:231], 0
	v_mfma_f32_16x16x32_bf16 v[72:75], v[196:199], v[236:239], 0
	v_mfma_f32_16x16x32_bf16 v[68:71], v[204:207], v[236:239], 0
	v_mfma_f32_16x16x32_bf16 v[120:123], v[200:203], v[216:219], v[120:123]
	v_mfma_f32_16x16x32_bf16 v[116:119], v[208:211], v[216:219], v[116:119]
	v_mfma_f32_16x16x32_bf16 v[104:107], v[200:203], v[224:227], v[104:107]
	v_mfma_f32_16x16x32_bf16 v[100:103], v[208:211], v[224:227], v[100:103]
	v_mfma_f32_16x16x32_bf16 v[88:91], v[200:203], v[232:235], v[88:91]
	v_mfma_f32_16x16x32_bf16 v[84:87], v[208:211], v[232:235], v[84:87]
	v_mfma_f32_16x16x32_bf16 v[72:75], v[200:203], v[240:243], v[72:75]
	v_mfma_f32_16x16x32_bf16 v[68:71], v[208:211], v[240:243], v[68:71]
	s_setprio 0
	s_barrier
	s_add_i32 s42, s64, s69
	s_mov_b32 m0, s42
	s_nop 0
	global_load_lds_dwordx4 v140, s[48:49]
	s_add_i32 m0, s42, 0x2000
	s_add_u32 s42, s48, s90
	s_addc_u32 s43, s49, 0
	s_add_i32 s64, s65, s69
	global_load_lds_dwordx4 v144, s[48:49]
	s_mov_b32 m0, s64
	s_nop 0
	global_load_lds_dwordx4 v140, s[42:43]
	s_add_i32 m0, s64, 0x2000
	s_nop 0
	global_load_lds_dwordx4 v144, s[42:43]
	ds_read_b128 v[212:215], v160 offset:16384
	ds_read_b128 v[216:219], v160 offset:17408
	ds_read_b128 v[220:223], v160 offset:18432
	ds_read_b128 v[224:227], v160 offset:19456
	ds_read_b128 v[228:231], v160 offset:20480
	ds_read_b128 v[232:235], v160 offset:21504
	ds_read_b128 v[236:239], v160 offset:22528
	ds_read_b128 v[240:243], v160 offset:23552
	s_waitcnt vmcnt(6)
	s_waitcnt lgkmcnt(0)
	s_barrier
	s_setprio 1
	s_waitcnt lgkmcnt(0)
	v_mfma_f32_16x16x32_bf16 v[64:67], v[164:167], v[212:215], 0
	v_mfma_f32_16x16x32_bf16 v[60:63], v[188:191], v[212:215], 0
	v_mfma_f32_16x16x32_bf16 v[48:51], v[164:167], v[220:223], 0
	v_mfma_f32_16x16x32_bf16 v[44:47], v[188:191], v[220:223], 0
	v_mfma_f32_16x16x32_bf16 v[32:35], v[164:167], v[228:231], 0
	v_mfma_f32_16x16x32_bf16 v[28:31], v[188:191], v[228:231], 0
	v_mfma_f32_16x16x32_bf16 v[16:19], v[164:167], v[236:239], 0
	v_mfma_f32_16x16x32_bf16 v[12:15], v[188:191], v[236:239], 0
	v_mfma_f32_16x16x32_bf16 v[64:67], v[168:171], v[216:219], v[64:67]
	v_mfma_f32_16x16x32_bf16 v[60:63], v[192:195], v[216:219], v[60:63]
	v_mfma_f32_16x16x32_bf16 v[48:51], v[168:171], v[224:227], v[48:51]
	v_mfma_f32_16x16x32_bf16 v[44:47], v[192:195], v[224:227], v[44:47]
	v_mfma_f32_16x16x32_bf16 v[32:35], v[168:171], v[232:235], v[32:35]
	v_mfma_f32_16x16x32_bf16 v[28:31], v[192:195], v[232:235], v[28:31]
	v_mfma_f32_16x16x32_bf16 v[16:19], v[168:171], v[240:243], v[16:19]
	v_mfma_f32_16x16x32_bf16 v[12:15], v[192:195], v[240:243], v[12:15]
	s_setprio 0
	s_setprio 1
	v_mfma_f32_16x16x32_bf16 v[56:59], v[196:199], v[212:215], 0
	v_mfma_f32_16x16x32_bf16 v[52:55], v[204:207], v[212:215], 0
	v_mfma_f32_16x16x32_bf16 v[40:43], v[196:199], v[220:223], 0
	v_mfma_f32_16x16x32_bf16 v[36:39], v[204:207], v[220:223], 0
	v_mfma_f32_16x16x32_bf16 v[24:27], v[196:199], v[228:231], 0
	v_mfma_f32_16x16x32_bf16 v[20:23], v[204:207], v[228:231], 0
	v_mfma_f32_16x16x32_bf16 v[8:11], v[196:199], v[236:239], 0
	v_mfma_f32_16x16x32_bf16 v[4:7], v[204:207], v[236:239], 0
	v_mfma_f32_16x16x32_bf16 v[56:59], v[200:203], v[216:219], v[56:59]
	v_mfma_f32_16x16x32_bf16 v[52:55], v[208:211], v[216:219], v[52:55]
	v_mfma_f32_16x16x32_bf16 v[40:43], v[200:203], v[224:227], v[40:43]
	v_mfma_f32_16x16x32_bf16 v[36:39], v[208:211], v[224:227], v[36:39]
	v_mfma_f32_16x16x32_bf16 v[24:27], v[200:203], v[232:235], v[24:27]
	v_mfma_f32_16x16x32_bf16 v[20:23], v[208:211], v[232:235], v[20:23]
	v_mfma_f32_16x16x32_bf16 v[8:11], v[200:203], v[240:243], v[8:11]
	v_mfma_f32_16x16x32_bf16 v[4:7], v[208:211], v[240:243], v[4:7]
	s_setprio 0
	s_barrier
	s_add_i32 s64, 0, 0x18000
	s_add_u32 s42, s50, s90
	s_addc_u32 s43, s51, 0
	s_mov_b32 m0, s56
	s_nop 0
	global_load_lds_dwordx4 v0, s[50:51]
	s_mov_b32 m0, s57
	s_nop 0
	global_load_lds_dwordx4 v142, s[50:51]
	v_add_u32_e32 v187, s64, v3
	s_add_i32 s65, 0, 0x1c000
	ds_read_b128 v[164:167], v187
	ds_read_b128 v[168:171], v187 offset:1024
	ds_read_b128 v[188:191], v187 offset:2048
	ds_read_b128 v[192:195], v187 offset:3072
	v_add_u32_e32 v187, s65, v3
	ds_read_b128 v[196:199], v187
	ds_read_b128 v[200:203], v187 offset:1024
	ds_read_b128 v[204:207], v187 offset:2048
	ds_read_b128 v[208:211], v187 offset:3072
	s_mov_b32 m0, s58
	s_nop 0
	global_load_lds_dwordx4 v0, s[42:43]
	s_mov_b32 m0, s59
	s_nop 0
	global_load_lds_dwordx4 v142, s[42:43]
	ds_read_b128 v[212:215], v160 offset:32768
	ds_read_b128 v[216:219], v160 offset:33792
	ds_read_b128 v[220:223], v160 offset:34816
	ds_read_b128 v[224:227], v160 offset:35840
	ds_read_b128 v[228:231], v160 offset:36864
	ds_read_b128 v[232:235], v160 offset:37888
	ds_read_b128 v[236:239], v160 offset:38912
	ds_read_b128 v[240:243], v160 offset:39936
	s_waitcnt vmcnt(8)
	s_waitcnt lgkmcnt(8)
	s_barrier
	s_setprio 1
	s_waitcnt lgkmcnt(0)
	v_mfma_f32_16x16x32_bf16 v[128:131], v[164:167], v[212:215], v[128:131]
	v_mfma_f32_16x16x32_bf16 v[124:127], v[188:191], v[212:215], v[124:127]
	v_mfma_f32_16x16x32_bf16 v[112:115], v[164:167], v[220:223], v[112:115]
	v_mfma_f32_16x16x32_bf16 v[108:111], v[188:191], v[220:223], v[108:111]
	v_mfma_f32_16x16x32_bf16 v[96:99], v[164:167], v[228:231], v[96:99]
	v_mfma_f32_16x16x32_bf16 v[92:95], v[188:191], v[228:231], v[92:95]
	v_mfma_f32_16x16x32_bf16 v[80:83], v[164:167], v[236:239], v[80:83]
	v_mfma_f32_16x16x32_bf16 v[76:79], v[188:191], v[236:239], v[76:79]
	v_mfma_f32_16x16x32_bf16 v[128:131], v[168:171], v[216:219], v[128:131]
	v_mfma_f32_16x16x32_bf16 v[124:127], v[192:195], v[216:219], v[124:127]
	v_mfma_f32_16x16x32_bf16 v[112:115], v[168:171], v[224:227], v[112:115]
	v_mfma_f32_16x16x32_bf16 v[108:111], v[192:195], v[224:227], v[108:111]
	v_mfma_f32_16x16x32_bf16 v[96:99], v[168:171], v[232:235], v[96:99]
	v_mfma_f32_16x16x32_bf16 v[92:95], v[192:195], v[232:235], v[92:95]
	v_mfma_f32_16x16x32_bf16 v[80:83], v[168:171], v[240:243], v[80:83]
	v_mfma_f32_16x16x32_bf16 v[76:79], v[192:195], v[240:243], v[76:79]
	s_setprio 0
	s_setprio 1
	v_mfma_f32_16x16x32_bf16 v[120:123], v[196:199], v[212:215], v[120:123]
	v_mfma_f32_16x16x32_bf16 v[116:119], v[204:207], v[212:215], v[116:119]
	v_mfma_f32_16x16x32_bf16 v[104:107], v[196:199], v[220:223], v[104:107]
	v_mfma_f32_16x16x32_bf16 v[100:103], v[204:207], v[220:223], v[100:103]
	v_mfma_f32_16x16x32_bf16 v[88:91], v[196:199], v[228:231], v[88:91]
	v_mfma_f32_16x16x32_bf16 v[84:87], v[204:207], v[228:231], v[84:87]
	v_mfma_f32_16x16x32_bf16 v[72:75], v[196:199], v[236:239], v[72:75]
	v_mfma_f32_16x16x32_bf16 v[68:71], v[204:207], v[236:239], v[68:71]
	v_mfma_f32_16x16x32_bf16 v[120:123], v[200:203], v[216:219], v[120:123]
	v_mfma_f32_16x16x32_bf16 v[116:119], v[208:211], v[216:219], v[116:119]
	v_mfma_f32_16x16x32_bf16 v[104:107], v[200:203], v[224:227], v[104:107]
	v_mfma_f32_16x16x32_bf16 v[100:103], v[208:211], v[224:227], v[100:103]
	v_mfma_f32_16x16x32_bf16 v[88:91], v[200:203], v[232:235], v[88:91]
	v_mfma_f32_16x16x32_bf16 v[84:87], v[208:211], v[232:235], v[84:87]
	v_mfma_f32_16x16x32_bf16 v[72:75], v[200:203], v[240:243], v[72:75]
	v_mfma_f32_16x16x32_bf16 v[68:71], v[208:211], v[240:243], v[68:71]
	s_setprio 0
	s_barrier
	s_add_u32 s42, s48, 0x80
	s_addc_u32 s43, s49, 0
	s_add_i32 s50, s64, s69
	s_mov_b32 m0, s50
	s_nop 0
	global_load_lds_dwordx4 v140, s[42:43]
	s_add_i32 m0, s50, 0x2000
	s_nop 0
	global_load_lds_dwordx4 v144, s[42:43]
	s_add_u32 s42, s48, s53
	s_addc_u32 s43, s49, 0
	s_add_i32 s48, s65, s69
	s_mov_b32 m0, s48
	s_nop 0
	global_load_lds_dwordx4 v140, s[42:43]
	s_add_i32 m0, s48, 0x2000
	s_nop 0
	global_load_lds_dwordx4 v144, s[42:43]
	ds_read_b128 v[212:215], v160 offset:49152
	ds_read_b128 v[216:219], v160 offset:50176
	ds_read_b128 v[220:223], v160 offset:51200
	ds_read_b128 v[224:227], v160 offset:52224
	ds_read_b128 v[228:231], v160 offset:53248
	ds_read_b128 v[232:235], v160 offset:54272
	ds_read_b128 v[236:239], v160 offset:55296
	ds_read_b128 v[240:243], v160 offset:56320
	s_waitcnt vmcnt(6)
	s_waitcnt lgkmcnt(0)
	s_barrier
	s_setprio 1
	s_waitcnt lgkmcnt(0)
	v_mfma_f32_16x16x32_bf16 v[64:67], v[164:167], v[212:215], v[64:67]
	v_mfma_f32_16x16x32_bf16 v[60:63], v[188:191], v[212:215], v[60:63]
	v_mfma_f32_16x16x32_bf16 v[48:51], v[164:167], v[220:223], v[48:51]
	v_mfma_f32_16x16x32_bf16 v[44:47], v[188:191], v[220:223], v[44:47]
	v_mfma_f32_16x16x32_bf16 v[32:35], v[164:167], v[228:231], v[32:35]
	v_mfma_f32_16x16x32_bf16 v[28:31], v[188:191], v[228:231], v[28:31]
	v_mfma_f32_16x16x32_bf16 v[16:19], v[164:167], v[236:239], v[16:19]
	v_mfma_f32_16x16x32_bf16 v[12:15], v[188:191], v[236:239], v[12:15]
	v_mfma_f32_16x16x32_bf16 v[64:67], v[168:171], v[216:219], v[64:67]
	v_mfma_f32_16x16x32_bf16 v[60:63], v[192:195], v[216:219], v[60:63]
	v_mfma_f32_16x16x32_bf16 v[48:51], v[168:171], v[224:227], v[48:51]
	v_mfma_f32_16x16x32_bf16 v[44:47], v[192:195], v[224:227], v[44:47]
	v_mfma_f32_16x16x32_bf16 v[32:35], v[168:171], v[232:235], v[32:35]
	v_mfma_f32_16x16x32_bf16 v[28:31], v[192:195], v[232:235], v[28:31]
	v_mfma_f32_16x16x32_bf16 v[16:19], v[168:171], v[240:243], v[16:19]
	v_mfma_f32_16x16x32_bf16 v[12:15], v[192:195], v[240:243], v[12:15]
	s_setprio 0
	s_setprio 1
	v_mfma_f32_16x16x32_bf16 v[56:59], v[196:199], v[212:215], v[56:59]
	v_mfma_f32_16x16x32_bf16 v[52:55], v[204:207], v[212:215], v[52:55]
	v_mfma_f32_16x16x32_bf16 v[40:43], v[196:199], v[220:223], v[40:43]
	v_mfma_f32_16x16x32_bf16 v[36:39], v[204:207], v[220:223], v[36:39]
	v_mfma_f32_16x16x32_bf16 v[24:27], v[196:199], v[228:231], v[24:27]
	v_mfma_f32_16x16x32_bf16 v[20:23], v[204:207], v[228:231], v[20:23]
	v_mfma_f32_16x16x32_bf16 v[8:11], v[196:199], v[236:239], v[8:11]
	v_mfma_f32_16x16x32_bf16 v[4:7], v[204:207], v[236:239], v[4:7]
	v_mfma_f32_16x16x32_bf16 v[56:59], v[200:203], v[216:219], v[56:59]
	v_mfma_f32_16x16x32_bf16 v[52:55], v[208:211], v[216:219], v[52:55]
	v_mfma_f32_16x16x32_bf16 v[40:43], v[200:203], v[224:227], v[40:43]
	v_mfma_f32_16x16x32_bf16 v[36:39], v[208:211], v[224:227], v[36:39]
	v_mfma_f32_16x16x32_bf16 v[24:27], v[200:203], v[232:235], v[24:27]
	v_mfma_f32_16x16x32_bf16 v[20:23], v[208:211], v[232:235], v[20:23]
	v_mfma_f32_16x16x32_bf16 v[8:11], v[200:203], v[240:243], v[8:11]
	v_mfma_f32_16x16x32_bf16 v[4:7], v[208:211], v[240:243], v[4:7]
	s_setprio 0
	s_barrier
	s_add_i32 s63, s63, 2
	s_add_u32 s28, s28, 0x100
	s_addc_u32 s29, s29, 0
	s_cmp_gt_u32 s63, s55
	s_mov_b64 s[42:43], s[44:45]

.Lg1_loop:
	s_add_u32 s44, s42, 0x100
	s_addc_u32 s45, s43, 0
	s_cmp_eq_u32 s63, s54
	s_cselect_b32 s50, s26, s44
	s_cselect_b32 s51, s5, s45
	s_cselect_b32 s48, s27, s28
	s_cselect_b32 s49, s23, s29
	s_add_i32 s64, 0, 0x10000
	s_add_u32 s46, s42, 0x80
	s_addc_u32 s47, s43, 0
	s_add_u32 s42, s42, s53
	s_addc_u32 s43, s43, 0
	s_mov_b32 m0, s60
	s_nop 0
	global_load_lds_dwordx4 v0, s[46:47]
	s_mov_b32 m0, s61
	s_nop 0
	global_load_lds_dwordx4 v142, s[46:47]
	v_add_u32_e32 v187, s64, v3
	s_add_i32 s65, 0, 0x14000
	ds_read_b128 v[164:167], v187
	ds_read_b128 v[168:171], v187 offset:1024
	ds_read_b128 v[188:191], v187 offset:2048
	ds_read_b128 v[192:195], v187 offset:3072
	v_add_u32_e32 v187, s65, v3
	ds_read_b128 v[196:199], v187
	ds_read_b128 v[200:203], v187 offset:1024
	ds_read_b128 v[204:207], v187 offset:2048
	ds_read_b128 v[208:211], v187 offset:3072
	s_add_i32 m0, s56, 0xc000
	s_nop 0
	global_load_lds_dwordx4 v0, s[42:43]
	s_add_i32 m0, s56, 0xe000
	s_nop 0
	global_load_lds_dwordx4 v142, s[42:43]
	ds_read_b128 v[212:215], v160
	ds_read_b128 v[216:219], v160 offset:1024
	ds_read_b128 v[220:223], v160 offset:2048
	ds_read_b128 v[224:227], v160 offset:3072
	ds_read_b128 v[228:231], v160 offset:4096
	ds_read_b128 v[232:235], v160 offset:5120
	ds_read_b128 v[236:239], v160 offset:6144
	ds_read_b128 v[240:243], v160 offset:7168
	s_waitcnt vmcnt(8)
	s_waitcnt lgkmcnt(8)
	s_barrier
	s_setprio 1
	s_waitcnt lgkmcnt(0)
	v_mfma_f32_16x16x32_bf16 v[128:131], v[164:167], v[212:215], v[128:131]
	v_mfma_f32_16x16x32_bf16 v[124:127], v[188:191], v[212:215], v[124:127]
	v_mfma_f32_16x16x32_bf16 v[112:115], v[164:167], v[220:223], v[112:115]
	v_mfma_f32_16x16x32_bf16 v[108:111], v[188:191], v[220:223], v[108:111]
	v_mfma_f32_16x16x32_bf16 v[96:99], v[164:167], v[228:231], v[96:99]
	v_mfma_f32_16x16x32_bf16 v[92:95], v[188:191], v[228:231], v[92:95]
	v_mfma_f32_16x16x32_bf16 v[80:83], v[164:167], v[236:239], v[80:83]
	v_mfma_f32_16x16x32_bf16 v[76:79], v[188:191], v[236:239], v[76:79]
	v_mfma_f32_16x16x32_bf16 v[128:131], v[168:171], v[216:219], v[128:131]
	v_mfma_f32_16x16x32_bf16 v[124:127], v[192:195], v[216:219], v[124:127]
	v_mfma_f32_16x16x32_bf16 v[112:115], v[168:171], v[224:227], v[112:115]
	v_mfma_f32_16x16x32_bf16 v[108:111], v[192:195], v[224:227], v[108:111]
	v_mfma_f32_16x16x32_bf16 v[96:99], v[168:171], v[232:235], v[96:99]
	v_mfma_f32_16x16x32_bf16 v[92:95], v[192:195], v[232:235], v[92:95]
	v_mfma_f32_16x16x32_bf16 v[80:83], v[168:171], v[240:243], v[80:83]
	v_mfma_f32_16x16x32_bf16 v[76:79], v[192:195], v[240:243], v[76:79]
	s_setprio 0
	s_setprio 1
	v_mfma_f32_16x16x32_bf16 v[120:123], v[196:199], v[212:215], v[120:123]
	v_mfma_f32_16x16x32_bf16 v[116:119], v[204:207], v[212:215], v[116:119]
	v_mfma_f32_16x16x32_bf16 v[104:107], v[196:199], v[220:223], v[104:107]
	v_mfma_f32_16x16x32_bf16 v[100:103], v[204:207], v[220:223], v[100:103]
	v_mfma_f32_16x16x32_bf16 v[88:91], v[196:199], v[228:231], v[88:91]
	v_mfma_f32_16x16x32_bf16 v[84:87], v[204:207], v[228:231], v[84:87]
	v_mfma_f32_16x16x32_bf16 v[72:75], v[196:199], v[236:239], v[72:75]
	v_mfma_f32_16x16x32_bf16 v[68:71], v[204:207], v[236:239], v[68:71]
	v_mfma_f32_16x16x32_bf16 v[120:123], v[200:203], v[216:219], v[120:123]
	v_mfma_f32_16x16x32_bf16 v[116:119], v[208:211], v[216:219], v[116:119]
	v_mfma_f32_16x16x32_bf16 v[104:107], v[200:203], v[224:227], v[104:107]
	v_mfma_f32_16x16x32_bf16 v[100:103], v[208:211], v[224:227], v[100:103]
	v_mfma_f32_16x16x32_bf16 v[88:91], v[200:203], v[232:235], v[88:91]
	v_mfma_f32_16x16x32_bf16 v[84:87], v[208:211], v[232:235], v[84:87]
	v_mfma_f32_16x16x32_bf16 v[72:75], v[200:203], v[240:243], v[72:75]
	v_mfma_f32_16x16x32_bf16 v[68:71], v[208:211], v[240:243], v[68:71]
	s_setprio 0
	s_barrier
	s_add_i32 s42, s64, s69
	s_mov_b32 m0, s42
	s_nop 0
	global_load_lds_dwordx4 v140, s[48:49]
	s_add_i32 m0, s42, 0x2000
	s_add_u32 s42, s48, s90
	s_addc_u32 s43, s49, 0
	s_add_i32 s64, s65, s69
	global_load_lds_dwordx4 v144, s[48:49]
	s_mov_b32 m0, s64
	s_nop 0
	global_load_lds_dwordx4 v140, s[42:43]
	s_add_i32 m0, s64, 0x2000
	s_nop 0
	global_load_lds_dwordx4 v144, s[42:43]
	ds_read_b128 v[212:215], v160 offset:16384
	ds_read_b128 v[216:219], v160 offset:17408
	ds_read_b128 v[220:223], v160 offset:18432
	ds_read_b128 v[224:227], v160 offset:19456
	ds_read_b128 v[228:231], v160 offset:20480
	ds_read_b128 v[232:235], v160 offset:21504
	ds_read_b128 v[236:239], v160 offset:22528
	ds_read_b128 v[240:243], v160 offset:23552
	s_waitcnt vmcnt(6)
	s_waitcnt lgkmcnt(0)
	s_barrier
	s_setprio 1
	s_waitcnt lgkmcnt(0)
	v_mfma_f32_16x16x32_bf16 v[64:67], v[164:167], v[212:215], v[64:67]
	v_mfma_f32_16x16x32_bf16 v[60:63], v[188:191], v[212:215], v[60:63]
	v_mfma_f32_16x16x32_bf16 v[48:51], v[164:167], v[220:223], v[48:51]
	v_mfma_f32_16x16x32_bf16 v[44:47], v[188:191], v[220:223], v[44:47]
	v_mfma_f32_16x16x32_bf16 v[32:35], v[164:167], v[228:231], v[32:35]
	v_mfma_f32_16x16x32_bf16 v[28:31], v[188:191], v[228:231], v[28:31]
	v_mfma_f32_16x16x32_bf16 v[16:19], v[164:167], v[236:239], v[16:19]
	v_mfma_f32_16x16x32_bf16 v[12:15], v[188:191], v[236:239], v[12:15]
	v_mfma_f32_16x16x32_bf16 v[64:67], v[168:171], v[216:219], v[64:67]
	v_mfma_f32_16x16x32_bf16 v[60:63], v[192:195], v[216:219], v[60:63]
	v_mfma_f32_16x16x32_bf16 v[48:51], v[168:171], v[224:227], v[48:51]
	v_mfma_f32_16x16x32_bf16 v[44:47], v[192:195], v[224:227], v[44:47]
	v_mfma_f32_16x16x32_bf16 v[32:35], v[168:171], v[232:235], v[32:35]
	v_mfma_f32_16x16x32_bf16 v[28:31], v[192:195], v[232:235], v[28:31]
	v_mfma_f32_16x16x32_bf16 v[16:19], v[168:171], v[240:243], v[16:19]
	v_mfma_f32_16x16x32_bf16 v[12:15], v[192:195], v[240:243], v[12:15]
	s_setprio 0
	s_setprio 1
	v_mfma_f32_16x16x32_bf16 v[56:59], v[196:199], v[212:215], v[56:59]
	v_mfma_f32_16x16x32_bf16 v[52:55], v[204:207], v[212:215], v[52:55]
	v_mfma_f32_16x16x32_bf16 v[40:43], v[196:199], v[220:223], v[40:43]
	v_mfma_f32_16x16x32_bf16 v[36:39], v[204:207], v[220:223], v[36:39]
	v_mfma_f32_16x16x32_bf16 v[24:27], v[196:199], v[228:231], v[24:27]
	v_mfma_f32_16x16x32_bf16 v[20:23], v[204:207], v[228:231], v[20:23]
	v_mfma_f32_16x16x32_bf16 v[8:11], v[196:199], v[236:239], v[8:11]
	v_mfma_f32_16x16x32_bf16 v[4:7], v[204:207], v[236:239], v[4:7]
	v_mfma_f32_16x16x32_bf16 v[56:59], v[200:203], v[216:219], v[56:59]
	v_mfma_f32_16x16x32_bf16 v[52:55], v[208:211], v[216:219], v[52:55]
	v_mfma_f32_16x16x32_bf16 v[40:43], v[200:203], v[224:227], v[40:43]
	v_mfma_f32_16x16x32_bf16 v[36:39], v[208:211], v[224:227], v[36:39]
	v_mfma_f32_16x16x32_bf16 v[24:27], v[200:203], v[232:235], v[24:27]
	v_mfma_f32_16x16x32_bf16 v[20:23], v[208:211], v[232:235], v[20:23]
	v_mfma_f32_16x16x32_bf16 v[8:11], v[200:203], v[240:243], v[8:11]
	v_mfma_f32_16x16x32_bf16 v[4:7], v[208:211], v[240:243], v[4:7]
	s_setprio 0
	s_barrier
	s_add_i32 s64, 0, 0x18000
	s_add_u32 s42, s50, s90
	s_addc_u32 s43, s51, 0
	s_mov_b32 m0, s56
	s_nop 0
	global_load_lds_dwordx4 v0, s[50:51]
	s_mov_b32 m0, s57
	s_nop 0
	global_load_lds_dwordx4 v142, s[50:51]
	v_add_u32_e32 v187, s64, v3
	s_add_i32 s65, 0, 0x1c000
	ds_read_b128 v[164:167], v187
	ds_read_b128 v[168:171], v187 offset:1024
	ds_read_b128 v[188:191], v187 offset:2048
	ds_read_b128 v[192:195], v187 offset:3072
	v_add_u32_e32 v187, s65, v3
	ds_read_b128 v[196:199], v187
	ds_read_b128 v[200:203], v187 offset:1024
	ds_read_b128 v[204:207], v187 offset:2048
	ds_read_b128 v[208:211], v187 offset:3072
	s_mov_b32 m0, s58
	s_nop 0
	global_load_lds_dwordx4 v0, s[42:43]
	s_mov_b32 m0, s59
	s_nop 0
	global_load_lds_dwordx4 v142, s[42:43]
	ds_read_b128 v[212:215], v160 offset:32768
	ds_read_b128 v[216:219], v160 offset:33792
	ds_read_b128 v[220:223], v160 offset:34816
	ds_read_b128 v[224:227], v160 offset:35840
	ds_read_b128 v[228:231], v160 offset:36864
	ds_read_b128 v[232:235], v160 offset:37888
	ds_read_b128 v[236:239], v160 offset:38912
	ds_read_b128 v[240:243], v160 offset:39936
	s_waitcnt vmcnt(8)
	s_waitcnt lgkmcnt(8)
	s_barrier
	s_setprio 1
	s_waitcnt lgkmcnt(0)
	v_mfma_f32_16x16x32_bf16 v[128:131], v[164:167], v[212:215], v[128:131]
	v_mfma_f32_16x16x32_bf16 v[124:127], v[188:191], v[212:215], v[124:127]
	v_mfma_f32_16x16x32_bf16 v[112:115], v[164:167], v[220:223], v[112:115]
	v_mfma_f32_16x16x32_bf16 v[108:111], v[188:191], v[220:223], v[108:111]
	v_mfma_f32_16x16x32_bf16 v[96:99], v[164:167], v[228:231], v[96:99]
	v_mfma_f32_16x16x32_bf16 v[92:95], v[188:191], v[228:231], v[92:95]
	v_mfma_f32_16x16x32_bf16 v[80:83], v[164:167], v[236:239], v[80:83]
	v_mfma_f32_16x16x32_bf16 v[76:79], v[188:191], v[236:239], v[76:79]
	v_mfma_f32_16x16x32_bf16 v[128:131], v[168:171], v[216:219], v[128:131]
	v_mfma_f32_16x16x32_bf16 v[124:127], v[192:195], v[216:219], v[124:127]
	v_mfma_f32_16x16x32_bf16 v[112:115], v[168:171], v[224:227], v[112:115]
	v_mfma_f32_16x16x32_bf16 v[108:111], v[192:195], v[224:227], v[108:111]
	v_mfma_f32_16x16x32_bf16 v[96:99], v[168:171], v[232:235], v[96:99]
	v_mfma_f32_16x16x32_bf16 v[92:95], v[192:195], v[232:235], v[92:95]
	v_mfma_f32_16x16x32_bf16 v[80:83], v[168:171], v[240:243], v[80:83]
	v_mfma_f32_16x16x32_bf16 v[76:79], v[192:195], v[240:243], v[76:79]
	s_setprio 0
	s_setprio 1
	v_mfma_f32_16x16x32_bf16 v[120:123], v[196:199], v[212:215], v[120:123]
	v_mfma_f32_16x16x32_bf16 v[116:119], v[204:207], v[212:215], v[116:119]
	v_mfma_f32_16x16x32_bf16 v[104:107], v[196:199], v[220:223], v[104:107]
	v_mfma_f32_16x16x32_bf16 v[100:103], v[204:207], v[220:223], v[100:103]
	v_mfma_f32_16x16x32_bf16 v[88:91], v[196:199], v[228:231], v[88:91]
	v_mfma_f32_16x16x32_bf16 v[84:87], v[204:207], v[228:231], v[84:87]
	v_mfma_f32_16x16x32_bf16 v[72:75], v[196:199], v[236:239], v[72:75]
	v_mfma_f32_16x16x32_bf16 v[68:71], v[204:207], v[236:239], v[68:71]
	v_mfma_f32_16x16x32_bf16 v[120:123], v[200:203], v[216:219], v[120:123]
	v_mfma_f32_16x16x32_bf16 v[116:119], v[208:211], v[216:219], v[116:119]
	v_mfma_f32_16x16x32_bf16 v[104:107], v[200:203], v[224:227], v[104:107]
	v_mfma_f32_16x16x32_bf16 v[100:103], v[208:211], v[224:227], v[100:103]
	v_mfma_f32_16x16x32_bf16 v[88:91], v[200:203], v[232:235], v[88:91]
	v_mfma_f32_16x16x32_bf16 v[84:87], v[208:211], v[232:235], v[84:87]
	v_mfma_f32_16x16x32_bf16 v[72:75], v[200:203], v[240:243], v[72:75]
	v_mfma_f32_16x16x32_bf16 v[68:71], v[208:211], v[240:243], v[68:71]
	s_setprio 0
	s_barrier
	s_add_u32 s42, s48, 0x80
	s_addc_u32 s43, s49, 0
	s_add_i32 s50, s64, s69
	s_mov_b32 m0, s50
	s_nop 0
	global_load_lds_dwordx4 v140, s[42:43]
	s_add_i32 m0, s50, 0x2000
	s_nop 0
	global_load_lds_dwordx4 v144, s[42:43]
	s_add_u32 s42, s48, s53
	s_addc_u32 s43, s49, 0
	s_add_i32 s48, s65, s69
	s_mov_b32 m0, s48
	s_nop 0
	global_load_lds_dwordx4 v140, s[42:43]
	s_add_i32 m0, s48, 0x2000
	s_nop 0
	global_load_lds_dwordx4 v144, s[42:43]
	ds_read_b128 v[212:215], v160 offset:49152
	ds_read_b128 v[216:219], v160 offset:50176
	ds_read_b128 v[220:223], v160 offset:51200
	ds_read_b128 v[224:227], v160 offset:52224
	ds_read_b128 v[228:231], v160 offset:53248
	ds_read_b128 v[232:235], v160 offset:54272
	ds_read_b128 v[236:239], v160 offset:55296
	ds_read_b128 v[240:243], v160 offset:56320
	s_waitcnt vmcnt(6)
	s_waitcnt lgkmcnt(0)
	s_barrier
	s_setprio 1
	s_waitcnt lgkmcnt(0)
	v_mfma_f32_16x16x32_bf16 v[64:67], v[164:167], v[212:215], v[64:67]
	v_mfma_f32_16x16x32_bf16 v[60:63], v[188:191], v[212:215], v[60:63]
	v_mfma_f32_16x16x32_bf16 v[48:51], v[164:167], v[220:223], v[48:51]
	v_mfma_f32_16x16x32_bf16 v[44:47], v[188:191], v[220:223], v[44:47]
	v_mfma_f32_16x16x32_bf16 v[32:35], v[164:167], v[228:231], v[32:35]
	v_mfma_f32_16x16x32_bf16 v[28:31], v[188:191], v[228:231], v[28:31]
	v_mfma_f32_16x16x32_bf16 v[16:19], v[164:167], v[236:239], v[16:19]
	v_mfma_f32_16x16x32_bf16 v[12:15], v[188:191], v[236:239], v[12:15]
	v_mfma_f32_16x16x32_bf16 v[64:67], v[168:171], v[216:219], v[64:67]
	v_mfma_f32_16x16x32_bf16 v[60:63], v[192:195], v[216:219], v[60:63]
	v_mfma_f32_16x16x32_bf16 v[48:51], v[168:171], v[224:227], v[48:51]
	v_mfma_f32_16x16x32_bf16 v[44:47], v[192:195], v[224:227], v[44:47]
	v_mfma_f32_16x16x32_bf16 v[32:35], v[168:171], v[232:235], v[32:35]
	v_mfma_f32_16x16x32_bf16 v[28:31], v[192:195], v[232:235], v[28:31]
	v_mfma_f32_16x16x32_bf16 v[16:19], v[168:171], v[240:243], v[16:19]
	v_mfma_f32_16x16x32_bf16 v[12:15], v[192:195], v[240:243], v[12:15]
	s_setprio 0
	s_setprio 1
	v_mfma_f32_16x16x32_bf16 v[56:59], v[196:199], v[212:215], v[56:59]
	v_mfma_f32_16x16x32_bf16 v[52:55], v[204:207], v[212:215], v[52:55]
	v_mfma_f32_16x16x32_bf16 v[40:43], v[196:199], v[220:223], v[40:43]
	v_mfma_f32_16x16x32_bf16 v[36:39], v[204:207], v[220:223], v[36:39]
	v_mfma_f32_16x16x32_bf16 v[24:27], v[196:199], v[228:231], v[24:27]
	v_mfma_f32_16x16x32_bf16 v[20:23], v[204:207], v[228:231], v[20:23]
	v_mfma_f32_16x16x32_bf16 v[8:11], v[196:199], v[236:239], v[8:11]
	v_mfma_f32_16x16x32_bf16 v[4:7], v[204:207], v[236:239], v[4:7]
	v_mfma_f32_16x16x32_bf16 v[56:59], v[200:203], v[216:219], v[56:59]
	v_mfma_f32_16x16x32_bf16 v[52:55], v[208:211], v[216:219], v[52:55]
	v_mfma_f32_16x16x32_bf16 v[40:43], v[200:203], v[224:227], v[40:43]
	v_mfma_f32_16x16x32_bf16 v[36:39], v[208:211], v[224:227], v[36:39]
	v_mfma_f32_16x16x32_bf16 v[24:27], v[200:203], v[232:235], v[24:27]
	v_mfma_f32_16x16x32_bf16 v[20:23], v[208:211], v[232:235], v[20:23]
	v_mfma_f32_16x16x32_bf16 v[8:11], v[200:203], v[240:243], v[8:11]
	v_mfma_f32_16x16x32_bf16 v[4:7], v[208:211], v[240:243], v[4:7]
	s_setprio 0
	s_barrier
	s_add_i32 s63, s63, 2
	s_add_u32 s28, s28, 0x100
	s_addc_u32 s29, s29, 0
	s_cmp_gt_u32 s63, s55
	s_mov_b64 s[42:43], s[44:45]
	s_cbranch_scc0 .Lg1_loop
	v_readlane_b32 s5, v250, 0
	v_readlane_b32 s23, v250, 1
	v_readlane_b32 s26, v250, 2
	v_readlane_b32 s27, v250, 3
	v_readlane_b32 s28, v250, 4
	v_readlane_b32 s29, v250, 5
	v_readlane_b32 s42, v250, 6
	v_readlane_b32 s43, v250, 7
	v_readlane_b32 s44, v250, 8
	v_readlane_b32 s45, v250, 9
	v_readlane_b32 s46, v250, 10
	v_readlane_b32 s47, v250, 11
	v_readlane_b32 s48, v250, 12
	v_readlane_b32 s49, v250, 13
	v_readlane_b32 s50, v250, 14
	v_readlane_b32 s51, v250, 15
	v_readlane_b32 s53, v250, 16
	v_readlane_b32 s54, v250, 17
	v_readlane_b32 s55, v250, 18
	v_readlane_b32 s56, v250, 19
	v_readlane_b32 s57, v250, 20
	v_readlane_b32 s58, v250, 21
	v_readlane_b32 s59, v250, 22
	v_readlane_b32 s60, v250, 23
	v_readlane_b32 s61, v250, 24
	v_readlane_b32 s63, v250, 25
	v_readlane_b32 s64, v250, 26
	v_readlane_b32 s65, v250, 27
	s_and_b64 vcc, exec, s[14:15]
	s_cbranch_vccz .LBB0_419
	s_barrier

.LBB0_499:
	s_ashr_i32 s5, s4, 31
	s_lshl_b64 s[24:25], s[4:5], 19
	s_add_u32 s24, s52, s24
	s_addc_u32 s25, s53, s25
	s_and_b64 s[26:27], s[40:41], exec
	s_cselect_b32 s5, s25, s43
	s_cselect_b32 s26, s24, s42
	s_ashr_i32 s23, s22, 31
	s_lshl_b64 s[28:29], s[22:23], 19
	s_add_u32 s36, s54, s28
	s_addc_u32 s37, s55, s29
	s_and_b64 s[28:29], s[40:41], exec
	s_cselect_b32 s23, s37, s45
	s_cselect_b32 s27, s36, s44
	s_add_u32 s28, s44, 0x100
	v_mov_b32_e32 v4, 0
	s_addc_u32 s29, s45, 0
	s_mov_b32 s63, -2
	s_add_u32 s44, s42, 0x100
	s_addc_u32 s45, s43, 0
	s_cmp_eq_u32 s63, 12
	s_cselect_b32 s50, s26, s44
	s_cselect_b32 s51, s5, s45
	s_cselect_b32 s48, s27, s28
	s_cselect_b32 s49, s23, s29
	s_add_i32 s64, 0, 0x10000
	s_add_u32 s46, s42, 0x80
	s_addc_u32 s47, s43, 0
	s_add_u32 s42, s42, 0x40080
	s_addc_u32 s43, s43, 0
	s_mov_b32 m0, s60
	s_nop 0
	global_load_lds_dwordx4 v144, s[46:47]
	s_mov_b32 m0, s61
	s_nop 0
	global_load_lds_dwordx4 v140, s[46:47]
	v_add_u32_e32 v138, s64, v3
	s_add_i32 s65, 0, 0x14000
	ds_read_b128 v[146:149], v138
	ds_read_b128 v[150:153], v138 offset:1024
	ds_read_b128 v[154:157], v138 offset:2048
	ds_read_b128 v[158:161], v138 offset:3072
	v_add_u32_e32 v138, s65, v3
	ds_read_b128 v[162:165], v138
	ds_read_b128 v[166:169], v138 offset:1024
	ds_read_b128 v[170:173], v138 offset:2048
	ds_read_b128 v[186:189], v138 offset:3072
	s_add_i32 m0, s56, 0xc000
	s_nop 0
	global_load_lds_dwordx4 v144, s[42:43]
	s_add_i32 m0, s56, 0xe000
	s_nop 0
	global_load_lds_dwordx4 v140, s[42:43]
	ds_read_b128 v[190:193], v132
	ds_read_b128 v[194:197], v132 offset:1024
	ds_read_b128 v[198:201], v132 offset:2048
	ds_read_b128 v[202:205], v132 offset:3072
	ds_read_b128 v[206:209], v132 offset:4096
	ds_read_b128 v[210:213], v132 offset:5120
	ds_read_b128 v[214:217], v132 offset:6144
	ds_read_b128 v[218:221], v132 offset:7168
	s_waitcnt vmcnt(8)
	s_waitcnt lgkmcnt(8)
	s_barrier
	s_setprio 1
	s_waitcnt lgkmcnt(0)
	v_mfma_f32_16x16x32_bf16 v[128:131], v[146:149], v[190:193], 0
	v_mfma_f32_16x16x32_bf16 v[124:127], v[154:157], v[190:193], 0
	v_mfma_f32_16x16x32_bf16 v[112:115], v[146:149], v[198:201], 0
	v_mfma_f32_16x16x32_bf16 v[108:111], v[154:157], v[198:201], 0
	v_mfma_f32_16x16x32_bf16 v[96:99], v[146:149], v[206:209], 0
	v_mfma_f32_16x16x32_bf16 v[92:95], v[154:157], v[206:209], 0
	v_mfma_f32_16x16x32_bf16 v[80:83], v[146:149], v[214:217], 0
	v_mfma_f32_16x16x32_bf16 v[76:79], v[154:157], v[214:217], 0
	v_mfma_f32_16x16x32_bf16 v[128:131], v[150:153], v[194:197], v[128:131]
	v_mfma_f32_16x16x32_bf16 v[124:127], v[158:161], v[194:197], v[124:127]
	v_mfma_f32_16x16x32_bf16 v[112:115], v[150:153], v[202:205], v[112:115]
	v_mfma_f32_16x16x32_bf16 v[108:111], v[158:161], v[202:205], v[108:111]
	v_mfma_f32_16x16x32_bf16 v[96:99], v[150:153], v[210:213], v[96:99]
	v_mfma_f32_16x16x32_bf16 v[92:95], v[158:161], v[210:213], v[92:95]
	v_mfma_f32_16x16x32_bf16 v[80:83], v[150:153], v[218:221], v[80:83]
	v_mfma_f32_16x16x32_bf16 v[76:79], v[158:161], v[218:221], v[76:79]
	s_setprio 0
	s_setprio 1
	v_mfma_f32_16x16x32_bf16 v[120:123], v[162:165], v[190:193], 0
	v_mfma_f32_16x16x32_bf16 v[116:119], v[170:173], v[190:193], 0
	v_mfma_f32_16x16x32_bf16 v[104:107], v[162:165], v[198:201], 0
	v_mfma_f32_16x16x32_bf16 v[100:103], v[170:173], v[198:201], 0
	v_mfma_f32_16x16x32_bf16 v[88:91], v[162:165], v[206:209], 0
	v_mfma_f32_16x16x32_bf16 v[84:87], v[170:173], v[206:209], 0
	v_mfma_f32_16x16x32_bf16 v[72:75], v[162:165], v[214:217], 0
	v_mfma_f32_16x16x32_bf16 v[68:71], v[170:173], v[214:217], 0
	v_mfma_f32_16x16x32_bf16 v[120:123], v[166:169], v[194:197], v[120:123]
	v_mfma_f32_16x16x32_bf16 v[116:119], v[186:189], v[194:197], v[116:119]
	v_mfma_f32_16x16x32_bf16 v[104:107], v[166:169], v[202:205], v[104:107]
	v_mfma_f32_16x16x32_bf16 v[100:103], v[186:189], v[202:205], v[100:103]
	v_mfma_f32_16x16x32_bf16 v[88:91], v[166:169], v[210:213], v[88:91]
	v_mfma_f32_16x16x32_bf16 v[84:87], v[186:189], v[210:213], v[84:87]
	v_mfma_f32_16x16x32_bf16 v[72:75], v[166:169], v[218:221], v[72:75]
	v_mfma_f32_16x16x32_bf16 v[68:71], v[186:189], v[218:221], v[68:71]
	s_setprio 0
	s_barrier
	s_add_i32 s42, s64, s69
	s_mov_b32 m0, s42
	s_nop 0
	global_load_lds_dwordx4 v142, s[48:49]
	s_add_i32 m0, s42, 0x2000
	s_add_u32 s42, s48, 0x40000
	s_addc_u32 s43, s49, 0
	s_add_i32 s64, s65, s69
	global_load_lds_dwordx4 v0, s[48:49]
	s_mov_b32 m0, s64
	s_nop 0
	global_load_lds_dwordx4 v142, s[42:43]
	s_add_i32 m0, s64, 0x2000
	s_nop 0
	global_load_lds_dwordx4 v0, s[42:43]
	ds_read_b128 v[190:193], v132 offset:16384
	ds_read_b128 v[194:197], v132 offset:17408
	ds_read_b128 v[198:201], v132 offset:18432
	ds_read_b128 v[202:205], v132 offset:19456
	ds_read_b128 v[206:209], v132 offset:20480
	ds_read_b128 v[210:213], v132 offset:21504
	ds_read_b128 v[214:217], v132 offset:22528
	ds_read_b128 v[218:221], v132 offset:23552
	s_waitcnt vmcnt(6)
	s_waitcnt lgkmcnt(0)
	s_barrier
	s_setprio 1
	s_waitcnt lgkmcnt(0)
	v_mfma_f32_16x16x32_bf16 v[64:67], v[146:149], v[190:193], 0
	v_mfma_f32_16x16x32_bf16 v[60:63], v[154:157], v[190:193], 0
	v_mfma_f32_16x16x32_bf16 v[48:51], v[146:149], v[198:201], 0
	v_mfma_f32_16x16x32_bf16 v[44:47], v[154:157], v[198:201], 0
	v_mfma_f32_16x16x32_bf16 v[32:35], v[146:149], v[206:209], 0
	v_mfma_f32_16x16x32_bf16 v[28:31], v[154:157], v[206:209], 0
	v_mfma_f32_16x16x32_bf16 v[16:19], v[146:149], v[214:217], 0
	v_mfma_f32_16x16x32_bf16 v[12:15], v[154:157], v[214:217], 0
	v_mfma_f32_16x16x32_bf16 v[64:67], v[150:153], v[194:197], v[64:67]
	v_mfma_f32_16x16x32_bf16 v[60:63], v[158:161], v[194:197], v[60:63]
	v_mfma_f32_16x16x32_bf16 v[48:51], v[150:153], v[202:205], v[48:51]
	v_mfma_f32_16x16x32_bf16 v[44:47], v[158:161], v[202:205], v[44:47]
	v_mfma_f32_16x16x32_bf16 v[32:35], v[150:153], v[210:213], v[32:35]
	v_mfma_f32_16x16x32_bf16 v[28:31], v[158:161], v[210:213], v[28:31]
	v_mfma_f32_16x16x32_bf16 v[16:19], v[150:153], v[218:221], v[16:19]
	v_mfma_f32_16x16x32_bf16 v[12:15], v[158:161], v[218:221], v[12:15]
	s_setprio 0
	s_setprio 1
	v_mfma_f32_16x16x32_bf16 v[56:59], v[162:165], v[190:193], 0
	v_mfma_f32_16x16x32_bf16 v[52:55], v[170:173], v[190:193], 0
	v_mfma_f32_16x16x32_bf16 v[40:43], v[162:165], v[198:201], 0
	v_mfma_f32_16x16x32_bf16 v[36:39], v[170:173], v[198:201], 0
	v_mfma_f32_16x16x32_bf16 v[24:27], v[162:165], v[206:209], 0
	v_mfma_f32_16x16x32_bf16 v[20:23], v[170:173], v[206:209], 0
	v_mfma_f32_16x16x32_bf16 v[8:11], v[162:165], v[214:217], 0
	v_mfma_f32_16x16x32_bf16 v[4:7], v[170:173], v[214:217], 0
	v_mfma_f32_16x16x32_bf16 v[56:59], v[166:169], v[194:197], v[56:59]
	v_mfma_f32_16x16x32_bf16 v[52:55], v[186:189], v[194:197], v[52:55]
	v_mfma_f32_16x16x32_bf16 v[40:43], v[166:169], v[202:205], v[40:43]
	v_mfma_f32_16x16x32_bf16 v[36:39], v[186:189], v[202:205], v[36:39]
	v_mfma_f32_16x16x32_bf16 v[24:27], v[166:169], v[210:213], v[24:27]
	v_mfma_f32_16x16x32_bf16 v[20:23], v[186:189], v[210:213], v[20:23]
	v_mfma_f32_16x16x32_bf16 v[8:11], v[166:169], v[218:221], v[8:11]
	v_mfma_f32_16x16x32_bf16 v[4:7], v[186:189], v[218:221], v[4:7]
	s_setprio 0
	s_barrier
	s_add_i32 s64, 0, 0x18000
	s_add_u32 s42, s50, 0x40000
	s_addc_u32 s43, s51, 0
	s_mov_b32 m0, s56
	s_nop 0
	global_load_lds_dwordx4 v144, s[50:51]
	s_mov_b32 m0, s57
	s_nop 0
	global_load_lds_dwordx4 v140, s[50:51]
	v_add_u32_e32 v138, s64, v3
	s_add_i32 s65, 0, 0x1c000
	ds_read_b128 v[146:149], v138
	ds_read_b128 v[150:153], v138 offset:1024
	ds_read_b128 v[154:157], v138 offset:2048
	ds_read_b128 v[158:161], v138 offset:3072
	v_add_u32_e32 v138, s65, v3
	ds_read_b128 v[162:165], v138
	ds_read_b128 v[166:169], v138 offset:1024
	ds_read_b128 v[170:173], v138 offset:2048
	ds_read_b128 v[186:189], v138 offset:3072
	s_mov_b32 m0, s58
	s_nop 0
	global_load_lds_dwordx4 v144, s[42:43]
	s_mov_b32 m0, s59
	s_nop 0
	global_load_lds_dwordx4 v140, s[42:43]
	ds_read_b128 v[190:193], v132 offset:32768
	ds_read_b128 v[194:197], v132 offset:33792
	ds_read_b128 v[198:201], v132 offset:34816
	ds_read_b128 v[202:205], v132 offset:35840
	ds_read_b128 v[206:209], v132 offset:36864
	ds_read_b128 v[210:213], v132 offset:37888
	ds_read_b128 v[214:217], v132 offset:38912
	ds_read_b128 v[218:221], v132 offset:39936
	s_waitcnt vmcnt(8)
	s_waitcnt lgkmcnt(8)
	s_barrier
	s_setprio 1
	s_waitcnt lgkmcnt(0)
	v_mfma_f32_16x16x32_bf16 v[128:131], v[146:149], v[190:193], v[128:131]
	v_mfma_f32_16x16x32_bf16 v[124:127], v[154:157], v[190:193], v[124:127]
	v_mfma_f32_16x16x32_bf16 v[112:115], v[146:149], v[198:201], v[112:115]
	v_mfma_f32_16x16x32_bf16 v[108:111], v[154:157], v[198:201], v[108:111]
	v_mfma_f32_16x16x32_bf16 v[96:99], v[146:149], v[206:209], v[96:99]
	v_mfma_f32_16x16x32_bf16 v[92:95], v[154:157], v[206:209], v[92:95]
	v_mfma_f32_16x16x32_bf16 v[80:83], v[146:149], v[214:217], v[80:83]
	v_mfma_f32_16x16x32_bf16 v[76:79], v[154:157], v[214:217], v[76:79]
	v_mfma_f32_16x16x32_bf16 v[128:131], v[150:153], v[194:197], v[128:131]
	v_mfma_f32_16x16x32_bf16 v[124:127], v[158:161], v[194:197], v[124:127]
	v_mfma_f32_16x16x32_bf16 v[112:115], v[150:153], v[202:205], v[112:115]
	v_mfma_f32_16x16x32_bf16 v[108:111], v[158:161], v[202:205], v[108:111]
	v_mfma_f32_16x16x32_bf16 v[96:99], v[150:153], v[210:213], v[96:99]
	v_mfma_f32_16x16x32_bf16 v[92:95], v[158:161], v[210:213], v[92:95]
	v_mfma_f32_16x16x32_bf16 v[80:83], v[150:153], v[218:221], v[80:83]
	v_mfma_f32_16x16x32_bf16 v[76:79], v[158:161], v[218:221], v[76:79]
	s_setprio 0
	s_setprio 1
	v_mfma_f32_16x16x32_bf16 v[120:123], v[162:165], v[190:193], v[120:123]
	v_mfma_f32_16x16x32_bf16 v[116:119], v[170:173], v[190:193], v[116:119]
	v_mfma_f32_16x16x32_bf16 v[104:107], v[162:165], v[198:201], v[104:107]
	v_mfma_f32_16x16x32_bf16 v[100:103], v[170:173], v[198:201], v[100:103]
	v_mfma_f32_16x16x32_bf16 v[88:91], v[162:165], v[206:209], v[88:91]
	v_mfma_f32_16x16x32_bf16 v[84:87], v[170:173], v[206:209], v[84:87]
	v_mfma_f32_16x16x32_bf16 v[72:75], v[162:165], v[214:217], v[72:75]
	v_mfma_f32_16x16x32_bf16 v[68:71], v[170:173], v[214:217], v[68:71]
	v_mfma_f32_16x16x32_bf16 v[120:123], v[166:169], v[194:197], v[120:123]
	v_mfma_f32_16x16x32_bf16 v[116:119], v[186:189], v[194:197], v[116:119]
	v_mfma_f32_16x16x32_bf16 v[104:107], v[166:169], v[202:205], v[104:107]
	v_mfma_f32_16x16x32_bf16 v[100:103], v[186:189], v[202:205], v[100:103]
	v_mfma_f32_16x16x32_bf16 v[88:91], v[166:169], v[210:213], v[88:91]
	v_mfma_f32_16x16x32_bf16 v[84:87], v[186:189], v[210:213], v[84:87]
	v_mfma_f32_16x16x32_bf16 v[72:75], v[166:169], v[218:221], v[72:75]
	v_mfma_f32_16x16x32_bf16 v[68:71], v[186:189], v[218:221], v[68:71]
	s_setprio 0
	s_barrier
	s_add_u32 s42, s48, 0x80
	s_addc_u32 s43, s49, 0
	s_add_i32 s50, s64, s69
	s_mov_b32 m0, s50
	s_nop 0
	global_load_lds_dwordx4 v142, s[42:43]
	s_add_i32 m0, s50, 0x2000
	s_nop 0
	global_load_lds_dwordx4 v0, s[42:43]
	s_add_u32 s42, s48, 0x40080
	s_addc_u32 s43, s49, 0
	s_add_i32 s48, s65, s69
	s_mov_b32 m0, s48
	s_nop 0
	global_load_lds_dwordx4 v142, s[42:43]
	s_add_i32 m0, s48, 0x2000
	s_nop 0
	global_load_lds_dwordx4 v0, s[42:43]
	ds_read_b128 v[190:193], v132 offset:49152
	ds_read_b128 v[194:197], v132 offset:50176
	ds_read_b128 v[198:201], v132 offset:51200
	ds_read_b128 v[202:205], v132 offset:52224
	ds_read_b128 v[206:209], v132 offset:53248
	ds_read_b128 v[210:213], v132 offset:54272
	ds_read_b128 v[214:217], v132 offset:55296
	ds_read_b128 v[218:221], v132 offset:56320
	s_waitcnt vmcnt(6)
	s_waitcnt lgkmcnt(0)
	s_barrier
	s_setprio 1
	s_waitcnt lgkmcnt(0)
	v_mfma_f32_16x16x32_bf16 v[64:67], v[146:149], v[190:193], v[64:67]
	v_mfma_f32_16x16x32_bf16 v[60:63], v[154:157], v[190:193], v[60:63]
	v_mfma_f32_16x16x32_bf16 v[48:51], v[146:149], v[198:201], v[48:51]
	v_mfma_f32_16x16x32_bf16 v[44:47], v[154:157], v[198:201], v[44:47]
	v_mfma_f32_16x16x32_bf16 v[32:35], v[146:149], v[206:209], v[32:35]
	v_mfma_f32_16x16x32_bf16 v[28:31], v[154:157], v[206:209], v[28:31]
	v_mfma_f32_16x16x32_bf16 v[16:19], v[146:149], v[214:217], v[16:19]
	v_mfma_f32_16x16x32_bf16 v[12:15], v[154:157], v[214:217], v[12:15]
	v_mfma_f32_16x16x32_bf16 v[64:67], v[150:153], v[194:197], v[64:67]
	v_mfma_f32_16x16x32_bf16 v[60:63], v[158:161], v[194:197], v[60:63]
	v_mfma_f32_16x16x32_bf16 v[48:51], v[150:153], v[202:205], v[48:51]
	v_mfma_f32_16x16x32_bf16 v[44:47], v[158:161], v[202:205], v[44:47]
	v_mfma_f32_16x16x32_bf16 v[32:35], v[150:153], v[210:213], v[32:35]
	v_mfma_f32_16x16x32_bf16 v[28:31], v[158:161], v[210:213], v[28:31]
	v_mfma_f32_16x16x32_bf16 v[16:19], v[150:153], v[218:221], v[16:19]
	v_mfma_f32_16x16x32_bf16 v[12:15], v[158:161], v[218:221], v[12:15]
	s_setprio 0
	s_setprio 1
	v_mfma_f32_16x16x32_bf16 v[56:59], v[162:165], v[190:193], v[56:59]
	v_mfma_f32_16x16x32_bf16 v[52:55], v[170:173], v[190:193], v[52:55]
	v_mfma_f32_16x16x32_bf16 v[40:43], v[162:165], v[198:201], v[40:43]
	v_mfma_f32_16x16x32_bf16 v[36:39], v[170:173], v[198:201], v[36:39]
	v_mfma_f32_16x16x32_bf16 v[24:27], v[162:165], v[206:209], v[24:27]
	v_mfma_f32_16x16x32_bf16 v[20:23], v[170:173], v[206:209], v[20:23]
	v_mfma_f32_16x16x32_bf16 v[8:11], v[162:165], v[214:217], v[8:11]
	v_mfma_f32_16x16x32_bf16 v[4:7], v[170:173], v[214:217], v[4:7]
	v_mfma_f32_16x16x32_bf16 v[56:59], v[166:169], v[194:197], v[56:59]
	v_mfma_f32_16x16x32_bf16 v[52:55], v[186:189], v[194:197], v[52:55]
	v_mfma_f32_16x16x32_bf16 v[40:43], v[166:169], v[202:205], v[40:43]
	v_mfma_f32_16x16x32_bf16 v[36:39], v[186:189], v[202:205], v[36:39]
	v_mfma_f32_16x16x32_bf16 v[24:27], v[166:169], v[210:213], v[24:27]
	v_mfma_f32_16x16x32_bf16 v[20:23], v[186:189], v[210:213], v[20:23]
	v_mfma_f32_16x16x32_bf16 v[8:11], v[166:169], v[218:221], v[8:11]
	v_mfma_f32_16x16x32_bf16 v[4:7], v[186:189], v[218:221], v[4:7]
	s_setprio 0
	s_barrier
	s_add_i32 s63, s63, 2
	s_add_u32 s28, s28, 0x100
	s_addc_u32 s29, s29, 0
	s_cmp_gt_u32 s63, 13
	s_mov_b64 s[42:43], s[44:45]

.LBB0_500:
	s_add_u32 s44, s42, 0x100
	s_addc_u32 s45, s43, 0
	s_cmp_eq_u32 s63, 12
	s_cselect_b32 s50, s26, s44
	s_cselect_b32 s51, s5, s45
	s_cselect_b32 s48, s27, s28
	s_cselect_b32 s49, s23, s29
	s_add_i32 s64, 0, 0x10000
	s_add_u32 s46, s42, 0x80
	s_addc_u32 s47, s43, 0
	s_add_u32 s42, s42, 0x40080
	s_addc_u32 s43, s43, 0
	s_mov_b32 m0, s60
	s_nop 0
	global_load_lds_dwordx4 v144, s[46:47]
	s_mov_b32 m0, s61
	s_nop 0
	global_load_lds_dwordx4 v140, s[46:47]
	v_add_u32_e32 v138, s64, v3
	s_add_i32 s65, 0, 0x14000
	ds_read_b128 v[146:149], v138
	ds_read_b128 v[150:153], v138 offset:1024
	ds_read_b128 v[154:157], v138 offset:2048
	ds_read_b128 v[158:161], v138 offset:3072
	v_add_u32_e32 v138, s65, v3
	ds_read_b128 v[162:165], v138
	ds_read_b128 v[166:169], v138 offset:1024
	ds_read_b128 v[170:173], v138 offset:2048
	ds_read_b128 v[186:189], v138 offset:3072
	s_add_i32 m0, s56, 0xc000
	s_nop 0
	global_load_lds_dwordx4 v144, s[42:43]
	s_add_i32 m0, s56, 0xe000
	s_nop 0
	global_load_lds_dwordx4 v140, s[42:43]
	ds_read_b128 v[190:193], v132
	ds_read_b128 v[194:197], v132 offset:1024
	ds_read_b128 v[198:201], v132 offset:2048
	ds_read_b128 v[202:205], v132 offset:3072
	ds_read_b128 v[206:209], v132 offset:4096
	ds_read_b128 v[210:213], v132 offset:5120
	ds_read_b128 v[214:217], v132 offset:6144
	ds_read_b128 v[218:221], v132 offset:7168
	s_waitcnt vmcnt(8)
	s_waitcnt lgkmcnt(8)
	s_barrier
	s_setprio 1
	s_waitcnt lgkmcnt(0)
	v_mfma_f32_16x16x32_bf16 v[128:131], v[146:149], v[190:193], v[128:131]
	v_mfma_f32_16x16x32_bf16 v[124:127], v[154:157], v[190:193], v[124:127]
	v_mfma_f32_16x16x32_bf16 v[112:115], v[146:149], v[198:201], v[112:115]
	v_mfma_f32_16x16x32_bf16 v[108:111], v[154:157], v[198:201], v[108:111]
	v_mfma_f32_16x16x32_bf16 v[96:99], v[146:149], v[206:209], v[96:99]
	v_mfma_f32_16x16x32_bf16 v[92:95], v[154:157], v[206:209], v[92:95]
	v_mfma_f32_16x16x32_bf16 v[80:83], v[146:149], v[214:217], v[80:83]
	v_mfma_f32_16x16x32_bf16 v[76:79], v[154:157], v[214:217], v[76:79]
	v_mfma_f32_16x16x32_bf16 v[128:131], v[150:153], v[194:197], v[128:131]
	v_mfma_f32_16x16x32_bf16 v[124:127], v[158:161], v[194:197], v[124:127]
	v_mfma_f32_16x16x32_bf16 v[112:115], v[150:153], v[202:205], v[112:115]
	v_mfma_f32_16x16x32_bf16 v[108:111], v[158:161], v[202:205], v[108:111]
	v_mfma_f32_16x16x32_bf16 v[96:99], v[150:153], v[210:213], v[96:99]
	v_mfma_f32_16x16x32_bf16 v[92:95], v[158:161], v[210:213], v[92:95]
	v_mfma_f32_16x16x32_bf16 v[80:83], v[150:153], v[218:221], v[80:83]
	v_mfma_f32_16x16x32_bf16 v[76:79], v[158:161], v[218:221], v[76:79]
	s_setprio 0
	s_setprio 1
	v_mfma_f32_16x16x32_bf16 v[120:123], v[162:165], v[190:193], v[120:123]
	v_mfma_f32_16x16x32_bf16 v[116:119], v[170:173], v[190:193], v[116:119]
	v_mfma_f32_16x16x32_bf16 v[104:107], v[162:165], v[198:201], v[104:107]
	v_mfma_f32_16x16x32_bf16 v[100:103], v[170:173], v[198:201], v[100:103]
	v_mfma_f32_16x16x32_bf16 v[88:91], v[162:165], v[206:209], v[88:91]
	v_mfma_f32_16x16x32_bf16 v[84:87], v[170:173], v[206:209], v[84:87]
	v_mfma_f32_16x16x32_bf16 v[72:75], v[162:165], v[214:217], v[72:75]
	v_mfma_f32_16x16x32_bf16 v[68:71], v[170:173], v[214:217], v[68:71]
	v_mfma_f32_16x16x32_bf16 v[120:123], v[166:169], v[194:197], v[120:123]
	v_mfma_f32_16x16x32_bf16 v[116:119], v[186:189], v[194:197], v[116:119]
	v_mfma_f32_16x16x32_bf16 v[104:107], v[166:169], v[202:205], v[104:107]
	v_mfma_f32_16x16x32_bf16 v[100:103], v[186:189], v[202:205], v[100:103]
	v_mfma_f32_16x16x32_bf16 v[88:91], v[166:169], v[210:213], v[88:91]
	v_mfma_f32_16x16x32_bf16 v[84:87], v[186:189], v[210:213], v[84:87]
	v_mfma_f32_16x16x32_bf16 v[72:75], v[166:169], v[218:221], v[72:75]
	v_mfma_f32_16x16x32_bf16 v[68:71], v[186:189], v[218:221], v[68:71]
	s_setprio 0
	s_barrier
	s_add_i32 s42, s64, s69
	s_mov_b32 m0, s42
	s_nop 0
	global_load_lds_dwordx4 v142, s[48:49]
	s_add_i32 m0, s42, 0x2000
	s_add_u32 s42, s48, 0x40000
	s_addc_u32 s43, s49, 0
	s_add_i32 s64, s65, s69
	global_load_lds_dwordx4 v0, s[48:49]
	s_mov_b32 m0, s64
	s_nop 0
	global_load_lds_dwordx4 v142, s[42:43]
	s_add_i32 m0, s64, 0x2000
	s_nop 0
	global_load_lds_dwordx4 v0, s[42:43]
	ds_read_b128 v[190:193], v132 offset:16384
	ds_read_b128 v[194:197], v132 offset:17408
	ds_read_b128 v[198:201], v132 offset:18432
	ds_read_b128 v[202:205], v132 offset:19456
	ds_read_b128 v[206:209], v132 offset:20480
	ds_read_b128 v[210:213], v132 offset:21504
	ds_read_b128 v[214:217], v132 offset:22528
	ds_read_b128 v[218:221], v132 offset:23552
	s_waitcnt vmcnt(6)
	s_waitcnt lgkmcnt(0)
	s_barrier
	s_setprio 1
	s_waitcnt lgkmcnt(0)
	v_mfma_f32_16x16x32_bf16 v[64:67], v[146:149], v[190:193], v[64:67]
	v_mfma_f32_16x16x32_bf16 v[60:63], v[154:157], v[190:193], v[60:63]
	v_mfma_f32_16x16x32_bf16 v[48:51], v[146:149], v[198:201], v[48:51]
	v_mfma_f32_16x16x32_bf16 v[44:47], v[154:157], v[198:201], v[44:47]
	v_mfma_f32_16x16x32_bf16 v[32:35], v[146:149], v[206:209], v[32:35]
	v_mfma_f32_16x16x32_bf16 v[28:31], v[154:157], v[206:209], v[28:31]
	v_mfma_f32_16x16x32_bf16 v[16:19], v[146:149], v[214:217], v[16:19]
	v_mfma_f32_16x16x32_bf16 v[12:15], v[154:157], v[214:217], v[12:15]
	v_mfma_f32_16x16x32_bf16 v[64:67], v[150:153], v[194:197], v[64:67]
	v_mfma_f32_16x16x32_bf16 v[60:63], v[158:161], v[194:197], v[60:63]
	v_mfma_f32_16x16x32_bf16 v[48:51], v[150:153], v[202:205], v[48:51]
	v_mfma_f32_16x16x32_bf16 v[44:47], v[158:161], v[202:205], v[44:47]
	v_mfma_f32_16x16x32_bf16 v[32:35], v[150:153], v[210:213], v[32:35]
	v_mfma_f32_16x16x32_bf16 v[28:31], v[158:161], v[210:213], v[28:31]
	v_mfma_f32_16x16x32_bf16 v[16:19], v[150:153], v[218:221], v[16:19]
	v_mfma_f32_16x16x32_bf16 v[12:15], v[158:161], v[218:221], v[12:15]
	s_setprio 0
	s_setprio 1
	v_mfma_f32_16x16x32_bf16 v[56:59], v[162:165], v[190:193], v[56:59]
	v_mfma_f32_16x16x32_bf16 v[52:55], v[170:173], v[190:193], v[52:55]
	v_mfma_f32_16x16x32_bf16 v[40:43], v[162:165], v[198:201], v[40:43]
	v_mfma_f32_16x16x32_bf16 v[36:39], v[170:173], v[198:201], v[36:39]
	v_mfma_f32_16x16x32_bf16 v[24:27], v[162:165], v[206:209], v[24:27]
	v_mfma_f32_16x16x32_bf16 v[20:23], v[170:173], v[206:209], v[20:23]
	v_mfma_f32_16x16x32_bf16 v[8:11], v[162:165], v[214:217], v[8:11]
	v_mfma_f32_16x16x32_bf16 v[4:7], v[170:173], v[214:217], v[4:7]
	v_mfma_f32_16x16x32_bf16 v[56:59], v[166:169], v[194:197], v[56:59]
	v_mfma_f32_16x16x32_bf16 v[52:55], v[186:189], v[194:197], v[52:55]
	v_mfma_f32_16x16x32_bf16 v[40:43], v[166:169], v[202:205], v[40:43]
	v_mfma_f32_16x16x32_bf16 v[36:39], v[186:189], v[202:205], v[36:39]
	v_mfma_f32_16x16x32_bf16 v[24:27], v[166:169], v[210:213], v[24:27]
	v_mfma_f32_16x16x32_bf16 v[20:23], v[186:189], v[210:213], v[20:23]
	v_mfma_f32_16x16x32_bf16 v[8:11], v[166:169], v[218:221], v[8:11]
	v_mfma_f32_16x16x32_bf16 v[4:7], v[186:189], v[218:221], v[4:7]
	s_setprio 0
	s_barrier
	s_add_i32 s64, 0, 0x18000
	s_add_u32 s42, s50, 0x40000
	s_addc_u32 s43, s51, 0
	s_mov_b32 m0, s56
	s_nop 0
	global_load_lds_dwordx4 v144, s[50:51]
	s_mov_b32 m0, s57
	s_nop 0
	global_load_lds_dwordx4 v140, s[50:51]
	v_add_u32_e32 v138, s64, v3
	s_add_i32 s65, 0, 0x1c000
	ds_read_b128 v[146:149], v138
	ds_read_b128 v[150:153], v138 offset:1024
	ds_read_b128 v[154:157], v138 offset:2048
	ds_read_b128 v[158:161], v138 offset:3072
	v_add_u32_e32 v138, s65, v3
	ds_read_b128 v[162:165], v138
	ds_read_b128 v[166:169], v138 offset:1024
	ds_read_b128 v[170:173], v138 offset:2048
	ds_read_b128 v[186:189], v138 offset:3072
	s_mov_b32 m0, s58
	s_nop 0
	global_load_lds_dwordx4 v144, s[42:43]
	s_mov_b32 m0, s59
	s_nop 0
	global_load_lds_dwordx4 v140, s[42:43]
	ds_read_b128 v[190:193], v132 offset:32768
	ds_read_b128 v[194:197], v132 offset:33792
	ds_read_b128 v[198:201], v132 offset:34816
	ds_read_b128 v[202:205], v132 offset:35840
	ds_read_b128 v[206:209], v132 offset:36864
	ds_read_b128 v[210:213], v132 offset:37888
	ds_read_b128 v[214:217], v132 offset:38912
	ds_read_b128 v[218:221], v132 offset:39936
	s_waitcnt vmcnt(8)
	s_waitcnt lgkmcnt(8)
	s_barrier
	s_setprio 1
	s_waitcnt lgkmcnt(0)
	v_mfma_f32_16x16x32_bf16 v[128:131], v[146:149], v[190:193], v[128:131]
	v_mfma_f32_16x16x32_bf16 v[124:127], v[154:157], v[190:193], v[124:127]
	v_mfma_f32_16x16x32_bf16 v[112:115], v[146:149], v[198:201], v[112:115]
	v_mfma_f32_16x16x32_bf16 v[108:111], v[154:157], v[198:201], v[108:111]
	v_mfma_f32_16x16x32_bf16 v[96:99], v[146:149], v[206:209], v[96:99]
	v_mfma_f32_16x16x32_bf16 v[92:95], v[154:157], v[206:209], v[92:95]
	v_mfma_f32_16x16x32_bf16 v[80:83], v[146:149], v[214:217], v[80:83]
	v_mfma_f32_16x16x32_bf16 v[76:79], v[154:157], v[214:217], v[76:79]
	v_mfma_f32_16x16x32_bf16 v[128:131], v[150:153], v[194:197], v[128:131]
	v_mfma_f32_16x16x32_bf16 v[124:127], v[158:161], v[194:197], v[124:127]
	v_mfma_f32_16x16x32_bf16 v[112:115], v[150:153], v[202:205], v[112:115]
	v_mfma_f32_16x16x32_bf16 v[108:111], v[158:161], v[202:205], v[108:111]
	v_mfma_f32_16x16x32_bf16 v[96:99], v[150:153], v[210:213], v[96:99]
	v_mfma_f32_16x16x32_bf16 v[92:95], v[158:161], v[210:213], v[92:95]
	v_mfma_f32_16x16x32_bf16 v[80:83], v[150:153], v[218:221], v[80:83]
	v_mfma_f32_16x16x32_bf16 v[76:79], v[158:161], v[218:221], v[76:79]
	s_setprio 0
	s_setprio 1
	v_mfma_f32_16x16x32_bf16 v[120:123], v[162:165], v[190:193], v[120:123]
	v_mfma_f32_16x16x32_bf16 v[116:119], v[170:173], v[190:193], v[116:119]
	v_mfma_f32_16x16x32_bf16 v[104:107], v[162:165], v[198:201], v[104:107]
	v_mfma_f32_16x16x32_bf16 v[100:103], v[170:173], v[198:201], v[100:103]
	v_mfma_f32_16x16x32_bf16 v[88:91], v[162:165], v[206:209], v[88:91]
	v_mfma_f32_16x16x32_bf16 v[84:87], v[170:173], v[206:209], v[84:87]
	v_mfma_f32_16x16x32_bf16 v[72:75], v[162:165], v[214:217], v[72:75]
	v_mfma_f32_16x16x32_bf16 v[68:71], v[170:173], v[214:217], v[68:71]
	v_mfma_f32_16x16x32_bf16 v[120:123], v[166:169], v[194:197], v[120:123]
	v_mfma_f32_16x16x32_bf16 v[116:119], v[186:189], v[194:197], v[116:119]
	v_mfma_f32_16x16x32_bf16 v[104:107], v[166:169], v[202:205], v[104:107]
	v_mfma_f32_16x16x32_bf16 v[100:103], v[186:189], v[202:205], v[100:103]
	v_mfma_f32_16x16x32_bf16 v[88:91], v[166:169], v[210:213], v[88:91]
	v_mfma_f32_16x16x32_bf16 v[84:87], v[186:189], v[210:213], v[84:87]
	v_mfma_f32_16x16x32_bf16 v[72:75], v[166:169], v[218:221], v[72:75]
	v_mfma_f32_16x16x32_bf16 v[68:71], v[186:189], v[218:221], v[68:71]
	s_setprio 0
	s_barrier
	s_add_u32 s42, s48, 0x80
	s_addc_u32 s43, s49, 0
	s_add_i32 s50, s64, s69
	s_mov_b32 m0, s50
	s_nop 0
	global_load_lds_dwordx4 v142, s[42:43]
	s_add_i32 m0, s50, 0x2000
	s_nop 0
	global_load_lds_dwordx4 v0, s[42:43]
	s_add_u32 s42, s48, 0x40080
	s_addc_u32 s43, s49, 0
	s_add_i32 s48, s65, s69
	s_mov_b32 m0, s48
	s_nop 0
	global_load_lds_dwordx4 v142, s[42:43]
	s_add_i32 m0, s48, 0x2000
	s_nop 0
	global_load_lds_dwordx4 v0, s[42:43]
	ds_read_b128 v[190:193], v132 offset:49152
	ds_read_b128 v[194:197], v132 offset:50176
	ds_read_b128 v[198:201], v132 offset:51200
	ds_read_b128 v[202:205], v132 offset:52224
	ds_read_b128 v[206:209], v132 offset:53248
	ds_read_b128 v[210:213], v132 offset:54272
	ds_read_b128 v[214:217], v132 offset:55296
	ds_read_b128 v[218:221], v132 offset:56320
	s_waitcnt vmcnt(6)
	s_waitcnt lgkmcnt(0)
	s_barrier
	s_setprio 1
	s_waitcnt lgkmcnt(0)
	v_mfma_f32_16x16x32_bf16 v[64:67], v[146:149], v[190:193], v[64:67]
	v_mfma_f32_16x16x32_bf16 v[60:63], v[154:157], v[190:193], v[60:63]
	v_mfma_f32_16x16x32_bf16 v[48:51], v[146:149], v[198:201], v[48:51]
	v_mfma_f32_16x16x32_bf16 v[44:47], v[154:157], v[198:201], v[44:47]
	v_mfma_f32_16x16x32_bf16 v[32:35], v[146:149], v[206:209], v[32:35]
	v_mfma_f32_16x16x32_bf16 v[28:31], v[154:157], v[206:209], v[28:31]
	v_mfma_f32_16x16x32_bf16 v[16:19], v[146:149], v[214:217], v[16:19]
	v_mfma_f32_16x16x32_bf16 v[12:15], v[154:157], v[214:217], v[12:15]
	v_mfma_f32_16x16x32_bf16 v[64:67], v[150:153], v[194:197], v[64:67]
	v_mfma_f32_16x16x32_bf16 v[60:63], v[158:161], v[194:197], v[60:63]
	v_mfma_f32_16x16x32_bf16 v[48:51], v[150:153], v[202:205], v[48:51]
	v_mfma_f32_16x16x32_bf16 v[44:47], v[158:161], v[202:205], v[44:47]
	v_mfma_f32_16x16x32_bf16 v[32:35], v[150:153], v[210:213], v[32:35]
	v_mfma_f32_16x16x32_bf16 v[28:31], v[158:161], v[210:213], v[28:31]
	v_mfma_f32_16x16x32_bf16 v[16:19], v[150:153], v[218:221], v[16:19]
	v_mfma_f32_16x16x32_bf16 v[12:15], v[158:161], v[218:221], v[12:15]
	s_setprio 0
	s_setprio 1
	v_mfma_f32_16x16x32_bf16 v[56:59], v[162:165], v[190:193], v[56:59]
	v_mfma_f32_16x16x32_bf16 v[52:55], v[170:173], v[190:193], v[52:55]
	v_mfma_f32_16x16x32_bf16 v[40:43], v[162:165], v[198:201], v[40:43]
	v_mfma_f32_16x16x32_bf16 v[36:39], v[170:173], v[198:201], v[36:39]
	v_mfma_f32_16x16x32_bf16 v[24:27], v[162:165], v[206:209], v[24:27]
	v_mfma_f32_16x16x32_bf16 v[20:23], v[170:173], v[206:209], v[20:23]
	v_mfma_f32_16x16x32_bf16 v[8:11], v[162:165], v[214:217], v[8:11]
	v_mfma_f32_16x16x32_bf16 v[4:7], v[170:173], v[214:217], v[4:7]
	v_mfma_f32_16x16x32_bf16 v[56:59], v[166:169], v[194:197], v[56:59]
	v_mfma_f32_16x16x32_bf16 v[52:55], v[186:189], v[194:197], v[52:55]
	v_mfma_f32_16x16x32_bf16 v[40:43], v[166:169], v[202:205], v[40:43]
	v_mfma_f32_16x16x32_bf16 v[36:39], v[186:189], v[202:205], v[36:39]
	v_mfma_f32_16x16x32_bf16 v[24:27], v[166:169], v[210:213], v[24:27]
	v_mfma_f32_16x16x32_bf16 v[20:23], v[186:189], v[210:213], v[20:23]
	v_mfma_f32_16x16x32_bf16 v[8:11], v[166:169], v[218:221], v[8:11]
	v_mfma_f32_16x16x32_bf16 v[4:7], v[186:189], v[218:221], v[4:7]
	s_setprio 0
	s_barrier
	s_add_i32 s63, s63, 2
	s_add_u32 s28, s28, 0x100
	s_addc_u32 s29, s29, 0
	s_cmp_gt_u32 s63, 13
	s_mov_b64 s[42:43], s[44:45]
	s_cbranch_scc0 .LBB0_500
	s_and_b64 vcc, exec, s[14:15]
	s_cbranch_vccz .LBB0_503
	s_barrier
